# scan loop unrolled by two with the current/next register sets swapped in the second copy (register renaming): the 59 per-step N->C register copies are gone
# speedup vs baseline: 1.0053x; 1.0053x over previous
; #define LAS __attribute__((address_space(3)))
; __device__ __forceinline__ void phase_gdn_scan(const int wid_s, CParams& p, LAS unsigned char* lds) {
;     ...
;     for (int chain = blockIdx.x; chain < 256; chain += gridDim.x) {
;         const int b = chain >> 4, h = (chain >> 2) & 3, sl = chain & 3;
;         for (int i = tid; i < 32 * 136; i += NTHREADS) St[i] = (h16)0.f;
;         f32x4 st[2] = {{0.f, 0.f, 0.f, 0.f}, {0.f, 0.f, 0.f, 0.f}};
;         const int vt = wave & 1, wq = wave >> 1;
;         __syncthreads();
;         int cur = 0;
;         h16x8 wf[4], qf[4], inf[2], kf[2][2]; h16x4 uu; float egl;
;         h16x8 wfn[4], qfn[4], infn[2], kfn[2][2]; h16x4 uun; float egln;
;     ...
;         SCAN_LOAD(wf, uu, qf, inf, kf, egl, 0);
;         for (int n = 0; n < 64; ++n) {
;             const int tc0 = b * SEQ + n * 64;
;             const LAS h16* Sc = St + cur * (32 * 136); LAS h16* Sn = St + (cur ^ 1) * (32 * 136);
;             { const int nn = n + 1 < 64 ? n + 1 : n; SCAN_LOAD(wfn, uun, qfn, infn, kfn, egln, nn); }
.LBB0_1284:
	s_or_b64 exec, exec, s[10:11]
	s_lshl_b32 s10, s18, 8
	s_and_b32 s10, s10, 0xfffff000
	v_add_u32_e32 v2, s10, v116
	v_mov_b64_e32 v[4:5], s[4:5]
	s_bfe_u32 s7, s18, 0x20002
	v_ashrrev_i32_e32 v3, 31, v2
	v_mad_i64_i32 v[4:5], s[12:13], v2, s86, v[4:5]
	s_ashr_i32 s11, s10, 4
	s_lshl_b32 s58, s7, 8
	s_lshl_b32 s12, s18, 6
	v_lshlrev_b64 v[2:3], 10, v[2:3]
	v_lshl_add_u64 v[4:5], v[4:5], 0, s[58:59]
	s_and_b32 s12, s12, 0xc0
	s_mov_b32 s13, s59
	v_lshl_add_u64 v[2:3], s[8:9], 0, v[2:3]
	s_or_b32 s20, s11, s7
	v_lshl_add_u64 v[10:11], v[4:5], 0, v[0:1]
	v_lshl_add_u64 v[4:5], v[4:5], 0, s[12:13]
	v_mov_b32_e32 v135, v1
	v_lshl_add_u64 v[2:3], v[2:3], 0, s[58:59]
	s_ashr_i32 s21, s20, 31
	v_lshl_add_u64 v[4:5], v[4:5], 0, v[134:135]
	v_mov_b32_e32 v137, v1
	v_lshl_add_u64 v[2:3], v[2:3], 0, v[0:1]
	s_lshl_b64 s[22:23], s[20:21], 13
	s_waitcnt lgkmcnt(0)
	s_barrier
	global_load_dwordx4 v[90:93], v[10:11], off offset:64
	global_load_dwordx4 v[98:101], v[10:11], off offset:128
	v_lshl_add_u64 v[4:5], v[4:5], 0, v[136:137]
	global_load_dwordx4 v[38:41], v[10:11], off offset:192
	global_load_dwordx2 v[140:141], v[4:5], off offset:1024
	global_load_dwordx4 v[94:97], v[2:3], off
	global_load_dwordx4 v[102:105], v[2:3], off offset:64
	global_load_dwordx4 v[106:109], v[2:3], off offset:128
	global_load_dwordx4 v[30:33], v[2:3], off offset:192
	v_lshl_add_u64 v[2:3], v[130:131], 0, s[22:23]
	s_lshl_b64 s[22:23], s[20:21], 7
	global_load_dwordx4 v[34:37], v[2:3], off
	global_load_dwordx4 v[26:29], v[2:3], off offset:64
	v_mov_b32_e32 v3, s23
	v_or_b32_e32 v2, s22, v114
	v_lshl_add_u64 v[4:5], v[2:3], 0, v[120:121]
	v_lshl_add_u64 v[2:3], v[2:3], 0, v[132:133]
	s_and_b32 s6, s17, 0xfffff000
	v_lshlrev_b64 v[4:5], 7, v[4:5]
	v_lshlrev_b64 v[2:3], 7, v[2:3]
	s_lshl_b64 s[20:21], s[20:21], 2
	v_lshl_add_u64 v[4:5], v[122:123], 0, v[4:5]
	v_lshl_add_u64 v[2:3], v[122:123], 0, v[2:3]
	s_add_u32 s20, s15, s20
	global_load_dwordx4 v[18:21], v[4:5], off
	global_load_dwordx4 v[14:17], v[4:5], off offset:64
	global_load_dwordx4 v[6:9], v[2:3], off
	s_nop 0
	global_load_dwordx4 v[2:5], v[2:3], off offset:64
	s_addc_u32 s21, s16, s21
	global_load_dwordx4 v[110:113], v[10:11], off
	global_load_dword v154, v1, s[20:21]
	v_lshl_add_u64 v[10:11], v[128:129], 0, s[58:59]
	s_add_u32 s11, s4, s58
	v_lshl_add_u64 v[10:11], v[10:11], 0, s[12:13]
	s_addc_u32 s13, s5, 0
	s_add_u32 s12, s11, s12
	s_addc_u32 s13, s13, 0
	v_lshl_add_u64 v[138:139], v[10:11], 0, v[134:135]
	v_lshl_add_u64 v[10:11], s[12:13], 0, v[134:135]
	v_lshl_add_u64 v[146:147], v[10:11], 0, v[136:137]
	v_mov_b32_e32 v10, 0
	v_add_u32_e32 v155, s6, v119
	v_mbcnt_lo_u32_b32 v177, -1, 0
	v_mbcnt_hi_u32_b32 v177, -1, v177
	v_and_b32_e32 v176, 15, v177
	v_lshrrev_b32_e32 v177, 4, v177
	v_lshlrev_b32_e32 v180, 2, v177
	v_sub_u32_e32 v180, v176, v180
	v_lshlrev_b32_e32 v177, 3, v177
	v_lshlrev_b32_e32 v176, 1, v176
	v_sub_u32_e32 v178, v177, v176
	v_ashrrev_i32_e32 v179, 31, v178
	v_lshl_add_u64 v[178:179], v[138:139], 0, v[178:179]
	v_add_u32_e32 v176, v155, v180
	v_mul_i32_i24_e32 v182, 0x10e, v180
	v_add_u32_e32 v161, s6, v152
	v_lshl_add_u64 v[142:143], v[124:125], 0, s[58:59]
	v_lshl_add_u64 v[144:145], v[126:127], 0, s[58:59]
	s_mov_b32 s12, 0
	s_mov_b32 s11, 0
	v_mov_b32_e32 v11, v10
	v_mov_b32_e32 v12, v10
	v_mov_b32_e32 v13, v10
	v_mov_b32_e32 v22, v10
	v_mov_b32_e32 v23, v10
	v_mov_b32_e32 v24, v10
	v_mov_b32_e32 v25, v10
	s_waitcnt vmcnt(0)
	v_mov_b64_e32 v[68:69], v[4:5]
	v_mov_b64_e32 v[66:67], v[2:3]
	v_mov_b64_e32 v[168:169], v[40:41]
	v_mov_b64_e32 v[166:167], v[38:39]
	v_mov_b64_e32 v[164:165], v[32:33]
	v_mov_b64_e32 v[162:163], v[30:31]
	v_mov_b64_e32 v[174:175], v[140:141]
	v_mov_b64_e32 v[88:89], v[36:37]
	v_mov_b64_e32 v[84:85], v[28:29]
	v_mov_b64_e32 v[86:87], v[34:35]
	v_mov_b64_e32 v[82:83], v[26:27]
	v_mov_b64_e32 v[80:81], v[20:21]
	v_mov_b64_e32 v[76:77], v[16:17]
	v_mov_b64_e32 v[72:73], v[8:9]
	v_mov_b64_e32 v[78:79], v[18:19]
	v_mov_b64_e32 v[74:75], v[14:15]
	v_mov_b64_e32 v[70:71], v[6:7]
	v_mov_b32_e32 v137, v154
.LBB0_1285:
	s_add_i32 s13, s12, 64
	v_add_u32_e32 v2, s12, v161
	s_add_i32 s19, s13, s6
	v_mad_i64_i32 v[4:5], s[20:21], v2, s86, v[142:143]
	s_ashr_i32 s22, s19, 4
	global_load_dwordx4 v[62:65], v[4:5], off
	global_load_dwordx4 v[58:61], v[4:5], off offset:64
	global_load_dwordx4 v[54:57], v[4:5], off offset:128
	global_load_dwordx4 v[38:41], v[4:5], off offset:192
	v_mad_i64_i32 v[4:5], s[20:21], v2, s86, v[146:147]
	v_ashrrev_i32_e32 v3, 31, v2
	s_or_b32 s20, s22, s7
	v_lshlrev_b64 v[2:3], 10, v[2:3]
	s_ashr_i32 s21, s20, 31
	v_lshl_add_u64 v[2:3], v[144:145], 0, v[2:3]
	s_lshl_b64 s[22:23], s[20:21], 13
	global_load_dwordx2 v[140:141], v[4:5], off offset:1024
	global_load_dwordx4 v[50:53], v[2:3], off
	global_load_dwordx4 v[46:49], v[2:3], off offset:64
	global_load_dwordx4 v[42:45], v[2:3], off offset:128
	global_load_dwordx4 v[30:33], v[2:3], off offset:192
	v_lshl_add_u64 v[2:3], v[130:131], 0, s[22:23]
	s_lshl_b64 s[22:23], s[20:21], 7
	global_load_dwordx4 v[34:37], v[2:3], off
	global_load_dwordx4 v[26:29], v[2:3], off offset:64
	v_mov_b32_e32 v3, s23
	v_or_b32_e32 v2, s22, v114
	v_lshl_add_u64 v[4:5], v[2:3], 0, v[120:121]
	v_lshl_add_u64 v[2:3], v[2:3], 0, v[132:133]
	s_mul_i32 s24, s11, 0x2200
	v_lshlrev_b64 v[4:5], 7, v[4:5]
	v_lshlrev_b64 v[2:3], 7, v[2:3]
	v_lshl_add_u64 v[4:5], v[122:123], 0, v[4:5]
	v_lshl_add_u64 v[2:3], v[122:123], 0, v[2:3]
	v_add_u32_e32 v135, s24, v117
	global_load_dwordx4 v[18:21], v[4:5], off
	global_load_dwordx4 v[14:17], v[4:5], off offset:64
	global_load_dwordx4 v[6:9], v[2:3], off
	s_nop 0
	global_load_dwordx4 v[2:5], v[2:3], off offset:64
	ds_read_b128 v[200:203], v135
	ds_read_b128 v[204:207], v135 offset:64
	ds_read_b128 v[208:211], v135 offset:128
	ds_read_b128 v[212:215], v135 offset:192
	s_xor_b32 s11, s11, 1
	s_lshl_b64 s[20:21], s[20:21], 2
	s_add_u32 s20, s15, s20
	s_addc_u32 s21, s16, s21
	global_load_dword v154, v1, s[20:21]
	s_waitcnt lgkmcnt(3)
; #define LAS __attribute__((address_space(3)))
; __device__ __forceinline__ f32x4 mma16(const h16x8 a, const h16x8 b, const f32x4 c) { return __builtin_amdgcn_mfma_f32_16x16x32_f16(a, b, c, 0, 0, 0); }
; __device__ __forceinline__ void phase_gdn_scan(const int wid_s, CParams& p, LAS unsigned char* lds) {
;     ...
;         for (int n = 0; n < 64; ++n) {
;             const int tc0 = b * SEQ + n * 64;
;             const LAS h16* Sc = St + cur * (32 * 136); LAS h16* Sn = St + (cur ^ 1) * (32 * 136);
;             { const int nn = n + 1 < 64 ? n + 1 : n; SCAN_LOAD(wfn, uun, qfn, infn, kfn, egln, nn); }
;             {
;                 f32x4 acc = {0.f, 0.f, 0.f, 0.f};
; #pragma unroll
;                 for (int ks = 0; ks < 4; ++ks) acc = mma16(*(const LAS h16x8*)(Sc + (16 * vt + lr) * 136 + 32 * ks + 8 * lq), wf[ks], acc);
; #pragma unroll
;                 for (int r = 0; r < 4; ++r) Vnt[(16 * vt + 4 * lq + r) * 72 + 16 * wq + lr] = (h16)((float)uu[r] - acc[r]);
;             }
;             __syncthreads();
;             {
;                 f32x4 acc = {0.f, 0.f, 0.f, 0.f};
; #pragma unroll
;                 for (int ks = 0; ks < 4; ++ks) acc = mma16(qf[ks], *(const LAS h16x8*)(Sc + (16 * vt + lr) * 136 + 32 * ks + 8 * lq), acc);
; #pragma unroll
;                 for (int ks = 0; ks < 2; ++ks) acc = mma16(inf[ks], *(const LAS h16x8*)(Vnt + (16 * vt + lr) * 72 + 32 * ks + 8 * lq), acc);
; #pragma unroll
;                 for (int r = 0; r < 4; ++r) y[(size_t)(tc0 + 16 * wq + 4 * lq + r) * D + 512 + h * 128 + 32 * sl + 16 * vt + lr] = (h16)acc[r];
;             }
; #pragma unroll
;             for (int i = 0; i < 2; ++i) {
;                 f32x4 acc = st[i] * __expf(egl);
; #pragma unroll
;                 for (int ks = 0; ks < 2; ++ks) acc = mma16(*(const LAS h16x8*)(Vnt + (16 * vt + lr) * 72 + 32 * ks + 8 * lq), kf[i][ks], acc);
;                 st[i] = acc;
; #pragma unroll
;                 for (int r = 0; r < 4; ++r) Sn[(16 * vt + 4 * lq + r) * 136 + 16 * (2 * wq + i) + lr] = (h16)acc[r];
;             }
;             __syncthreads();
	v_mfma_f32_16x16x32_f16 v[110:113], v[200:203], v[110:113], 0
	s_waitcnt lgkmcnt(2)
	v_mfma_f32_16x16x32_f16 v[90:93], v[204:207], v[90:93], v[110:113]
	s_waitcnt lgkmcnt(1)
	v_mfma_f32_16x16x32_f16 v[90:93], v[208:211], v[98:101], v[90:93]
	s_waitcnt lgkmcnt(0)
	v_mfma_f32_16x16x32_f16 v[90:93], v[212:215], v[166:169], v[90:93]
	v_mfma_f32_16x16x32_f16 v[184:187], v[200:203], v[94:97], 0
	v_mfma_f32_16x16x32_f16 v[184:187], v[204:207], v[102:105], v[184:187]
	v_mfma_f32_16x16x32_f16 v[184:187], v[208:211], v[106:109], v[184:187]
	v_mfma_f32_16x16x32_f16 v[184:187], v[212:215], v[162:165], v[184:187]
	v_cvt_f32_f16_e32 v98, v174
	s_mul_i32 s19, s11, 0x2200
	s_cmpk_eq_i32 s13, 0xfc0
	s_nop 0
	s_nop 0
	s_nop 2
	v_sub_f32_e32 v90, v98, v90
	v_cvt_f16_f32_e32 v90, v90
	s_nop 0
	s_nop 0
	s_nop 0
	ds_write_b16 v153, v90 offset:17408
	v_cvt_f32_f16_sdwa v90, v174 dst_sel:DWORD dst_unused:UNUSED_PAD src0_sel:WORD_1
	s_nop 0
	s_nop 0
	s_nop 0
	s_nop 0
	v_sub_f32_e32 v90, v90, v91
	v_cvt_f16_f32_e32 v90, v90
	s_nop 0
	ds_write_b16 v153, v90 offset:17552
	v_cvt_f32_f16_e32 v90, v175
	v_sub_f32_e32 v90, v90, v92
	v_cvt_f16_f32_e32 v90, v90
	ds_write_b16 v153, v90 offset:17696
	v_cvt_f32_f16_sdwa v90, v175 dst_sel:DWORD dst_unused:UNUSED_PAD src0_sel:WORD_1
	v_sub_f32_e32 v90, v90, v93
	v_cvt_f16_f32_e32 v90, v90
	ds_write_b16 v153, v90 offset:17840
	s_waitcnt lgkmcnt(0)
	s_barrier
	v_add_u32_e32 v135, v115, v118
	ds_read_b128 v[94:97], v135 offset:17408
	ds_read_b128 v[90:93], v135 offset:17472
	s_waitcnt lgkmcnt(1)
	v_mfma_f32_16x16x32_f16 v[86:89], v[94:97], v[86:89], v[184:187]
	s_waitcnt lgkmcnt(0)
	v_mfma_f32_16x16x32_f16 v[82:85], v[90:93], v[82:85], v[86:89]
	s_nop 2
	v_add_u32_e32 v86, s12, v176
	v_ashrrev_i32_e32 v87, 31, v86
	v_lshlrev_b64 v[88:89], 11, v[86:87]
	s_nop 1
	v_lshl_add_u64 v[88:89], v[178:179], 0, v[88:89]
	v_cvt_pk_f16_f32 v82, v82, v83
	v_cvt_pk_f16_f32 v83, v84, v85
	global_store_dwordx2 v[88:89], v[82:83], off
	v_mul_f32_e32 v82, 0x3fb8aa3b, v137
	v_exp_f32_e32 v82, v82
	s_mov_b32 s12, s13
	s_nop 0
	v_pk_mul_f32 v[24:25], v[24:25], v[82:83] op_sel_hi:[1,0]
	v_pk_mul_f32 v[22:23], v[22:23], v[82:83] op_sel_hi:[1,0]
	v_pk_mul_f32 v[12:13], v[12:13], v[82:83] op_sel_hi:[1,0]
	v_pk_mul_f32 v[10:11], v[10:11], v[82:83] op_sel_hi:[1,0]
	v_mfma_f32_16x16x32_f16 v[22:25], v[78:81], v[94:97], v[22:25]
	v_add3_u32 v78, v148, s19, v149
	s_nop 0
	s_nop 0
	v_mfma_f32_16x16x32_f16 v[22:25], v[74:77], v[90:93], v[22:25]
	v_mfma_f32_16x16x32_f16 v[10:13], v[70:73], v[94:97], v[10:13]
	v_mfma_f32_16x16x32_f16 v[10:13], v[66:69], v[90:93], v[10:13]
	s_nop 0
	s_nop 0
	s_nop 0
	s_nop 0
	s_nop 0
	s_nop 2
	v_add_u32_e32 v78, v78, v182
	v_cvt_pk_f16_f32 v74, v22, v23
	v_cvt_pk_f16_f32 v75, v24, v25
	ds_write_b64 v78, v[74:75]
	s_nop 7
	v_cvt_pk_f16_f32 v66, v10, v11
	v_cvt_pk_f16_f32 v67, v12, v13
	ds_write_b64 v78, v[66:67] offset:32
	s_waitcnt vmcnt(1)
	s_waitcnt lgkmcnt(0)
	s_barrier
	s_cbranch_scc1 .Lscan_in_n
	s_add_i32 s13, s12, 64
	v_add_u32_e32 v66, s12, v161
	s_add_i32 s19, s13, s6
	v_mad_i64_i32 v[68:69], s[20:21], v66, s86, v[142:143]
	s_ashr_i32 s22, s19, 4
	global_load_dwordx4 v[110:113], v[68:69], off
	global_load_dwordx4 v[90:93], v[68:69], off offset:64
	global_load_dwordx4 v[98:101], v[68:69], off offset:128
	global_load_dwordx4 v[166:169], v[68:69], off offset:192
	v_mad_i64_i32 v[68:69], s[20:21], v66, s86, v[146:147]
	v_ashrrev_i32_e32 v67, 31, v66
	s_or_b32 s20, s22, s7
	v_lshlrev_b64 v[66:67], 10, v[66:67]
	s_ashr_i32 s21, s20, 31
	v_lshl_add_u64 v[66:67], v[144:145], 0, v[66:67]
	s_lshl_b64 s[22:23], s[20:21], 13
	global_load_dwordx2 v[174:175], v[68:69], off offset:1024
	global_load_dwordx4 v[94:97], v[66:67], off
	global_load_dwordx4 v[102:105], v[66:67], off offset:64
	global_load_dwordx4 v[106:109], v[66:67], off offset:128
	global_load_dwordx4 v[162:165], v[66:67], off offset:192
	v_lshl_add_u64 v[66:67], v[130:131], 0, s[22:23]
	s_lshl_b64 s[22:23], s[20:21], 7
	global_load_dwordx4 v[86:89], v[66:67], off
	global_load_dwordx4 v[82:85], v[66:67], off offset:64
	v_mov_b32_e32 v67, s23
	v_or_b32_e32 v66, s22, v114
	v_lshl_add_u64 v[68:69], v[66:67], 0, v[120:121]
	v_lshl_add_u64 v[66:67], v[66:67], 0, v[132:133]
	s_mul_i32 s24, s11, 0x2200
	v_lshlrev_b64 v[68:69], 7, v[68:69]
	v_lshlrev_b64 v[66:67], 7, v[66:67]
	v_lshl_add_u64 v[68:69], v[122:123], 0, v[68:69]
	v_lshl_add_u64 v[66:67], v[122:123], 0, v[66:67]
	v_add_u32_e32 v135, s24, v117
	global_load_dwordx4 v[78:81], v[68:69], off
	global_load_dwordx4 v[74:77], v[68:69], off offset:64
	global_load_dwordx4 v[70:73], v[66:67], off
	s_nop 0
	global_load_dwordx4 v[66:69], v[66:67], off offset:64
	ds_read_b128 v[200:203], v135
	ds_read_b128 v[204:207], v135 offset:64
	ds_read_b128 v[208:211], v135 offset:128
	ds_read_b128 v[212:215], v135 offset:192
	s_xor_b32 s11, s11, 1
	s_lshl_b64 s[20:21], s[20:21], 2
	s_add_u32 s20, s15, s20
	s_addc_u32 s21, s16, s21
	global_load_dword v137, v1, s[20:21]
	s_waitcnt lgkmcnt(3)
	v_mfma_f32_16x16x32_f16 v[62:65], v[200:203], v[62:65], 0
	s_waitcnt lgkmcnt(2)
	v_mfma_f32_16x16x32_f16 v[58:61], v[204:207], v[58:61], v[62:65]
	s_waitcnt lgkmcnt(1)
	v_mfma_f32_16x16x32_f16 v[58:61], v[208:211], v[54:57], v[58:61]
	s_waitcnt lgkmcnt(0)
	v_mfma_f32_16x16x32_f16 v[58:61], v[212:215], v[38:41], v[58:61]
	v_mfma_f32_16x16x32_f16 v[184:187], v[200:203], v[50:53], 0
	v_mfma_f32_16x16x32_f16 v[184:187], v[204:207], v[46:49], v[184:187]
	v_mfma_f32_16x16x32_f16 v[184:187], v[208:211], v[42:45], v[184:187]
	v_mfma_f32_16x16x32_f16 v[184:187], v[212:215], v[30:33], v[184:187]
	v_cvt_f32_f16_e32 v54, v140
	s_mul_i32 s19, s11, 0x2200
	s_cmpk_eq_i32 s13, 0xfc0
	s_nop 0
	s_nop 0
	s_nop 2
	v_sub_f32_e32 v58, v54, v58
	v_cvt_f16_f32_e32 v58, v58
	s_nop 0
	s_nop 0
	s_nop 0
	ds_write_b16 v153, v58 offset:17408
	v_cvt_f32_f16_sdwa v58, v140 dst_sel:DWORD dst_unused:UNUSED_PAD src0_sel:WORD_1
	s_nop 0
	s_nop 0
	s_nop 0
	s_nop 0
	v_sub_f32_e32 v58, v58, v59
	v_cvt_f16_f32_e32 v58, v58
	s_nop 0
	ds_write_b16 v153, v58 offset:17552
	v_cvt_f32_f16_e32 v58, v141
	v_sub_f32_e32 v58, v58, v60
	v_cvt_f16_f32_e32 v58, v58
	ds_write_b16 v153, v58 offset:17696
	v_cvt_f32_f16_sdwa v58, v141 dst_sel:DWORD dst_unused:UNUSED_PAD src0_sel:WORD_1
	v_sub_f32_e32 v58, v58, v61
	v_cvt_f16_f32_e32 v58, v58
	ds_write_b16 v153, v58 offset:17840
	s_waitcnt lgkmcnt(0)
	s_barrier
; #define LAS __attribute__((address_space(3)))
; __device__ __forceinline__ f32x4 mma16(const h16x8 a, const h16x8 b, const f32x4 c) { return __builtin_amdgcn_mfma_f32_16x16x32_f16(a, b, c, 0, 0, 0); }
; __device__ __forceinline__ void phase_gdn_scan(const int wid_s, CParams& p, LAS unsigned char* lds) {
;     ...
;             __syncthreads();
;             {
;                 f32x4 acc = {0.f, 0.f, 0.f, 0.f};
; #pragma unroll
;                 for (int ks = 0; ks < 4; ++ks) acc = mma16(qf[ks], *(const LAS h16x8*)(Sc + (16 * vt + lr) * 136 + 32 * ks + 8 * lq), acc);
; #pragma unroll
;                 for (int ks = 0; ks < 2; ++ks) acc = mma16(inf[ks], *(const LAS h16x8*)(Vnt + (16 * vt + lr) * 72 + 32 * ks + 8 * lq), acc);
; #pragma unroll
;                 for (int r = 0; r < 4; ++r) y[(size_t)(tc0 + 16 * wq + 4 * lq + r) * D + 512 + h * 128 + 32 * sl + 16 * vt + lr] = (h16)acc[r];
;             }
; #pragma unroll
;             for (int i = 0; i < 2; ++i) {
;                 f32x4 acc = st[i] * __expf(egl);
; #pragma unroll
;                 for (int ks = 0; ks < 2; ++ks) acc = mma16(*(const LAS h16x8*)(Vnt + (16 * vt + lr) * 72 + 32 * ks + 8 * lq), kf[i][ks], acc);
;                 st[i] = acc;
; #pragma unroll
;                 for (int r = 0; r < 4; ++r) Sn[(16 * vt + 4 * lq + r) * 136 + 16 * (2 * wq + i) + lr] = (h16)acc[r];
;             }
;             __syncthreads();
;             cur ^= 1;
; #pragma unroll
;             for (int ks = 0; ks < 4; ++ks) { wf[ks] = wfn[ks]; qf[ks] = qfn[ks]; }
; #pragma unroll
;             for (int ks = 0; ks < 2; ++ks) { inf[ks] = infn[ks]; kf[0][ks] = kfn[0][ks]; kf[1][ks] = kfn[1][ks]; }
;             uu = uun; egl = egln;
	v_add_u32_e32 v135, v115, v118
	ds_read_b128 v[50:53], v135 offset:17408
	ds_read_b128 v[58:61], v135 offset:17472
	s_waitcnt lgkmcnt(1)
	v_mfma_f32_16x16x32_f16 v[34:37], v[50:53], v[34:37], v[184:187]
	s_waitcnt lgkmcnt(0)
	v_mfma_f32_16x16x32_f16 v[26:29], v[58:61], v[26:29], v[34:37]
	s_nop 2
	v_add_u32_e32 v34, s12, v176
	v_ashrrev_i32_e32 v35, 31, v34
	v_lshlrev_b64 v[36:37], 11, v[34:35]
	s_nop 1
	v_lshl_add_u64 v[36:37], v[178:179], 0, v[36:37]
	v_cvt_pk_f16_f32 v26, v26, v27
	v_cvt_pk_f16_f32 v27, v28, v29
	global_store_dwordx2 v[36:37], v[26:27], off
	v_mul_f32_e32 v26, 0x3fb8aa3b, v154
	v_exp_f32_e32 v26, v26
	s_mov_b32 s12, s13
	s_nop 0
	v_pk_mul_f32 v[24:25], v[24:25], v[26:27] op_sel_hi:[1,0]
	v_pk_mul_f32 v[22:23], v[22:23], v[26:27] op_sel_hi:[1,0]
	v_pk_mul_f32 v[12:13], v[12:13], v[26:27] op_sel_hi:[1,0]
	v_pk_mul_f32 v[10:11], v[10:11], v[26:27] op_sel_hi:[1,0]
	v_mfma_f32_16x16x32_f16 v[22:25], v[18:21], v[50:53], v[22:25]
	v_add3_u32 v18, v148, s19, v149
	s_nop 0
	s_nop 0
	v_mfma_f32_16x16x32_f16 v[22:25], v[14:17], v[58:61], v[22:25]
	v_mfma_f32_16x16x32_f16 v[10:13], v[6:9], v[50:53], v[10:13]
	v_mfma_f32_16x16x32_f16 v[10:13], v[2:5], v[58:61], v[10:13]
	s_nop 0
	s_nop 0
	s_nop 0
	s_nop 0
	s_nop 0
	s_nop 2
	v_add_u32_e32 v18, v18, v182
	v_cvt_pk_f16_f32 v14, v22, v23
	v_cvt_pk_f16_f32 v15, v24, v25
	ds_write_b64 v18, v[14:15]
	s_nop 7
	v_cvt_pk_f16_f32 v2, v10, v11
	v_cvt_pk_f16_f32 v3, v12, v13
	ds_write_b64 v18, v[2:3] offset:32
	s_waitcnt vmcnt(1)
	s_waitcnt lgkmcnt(0)
	s_barrier
	s_cbranch_scc0 .LBB0_1285
	v_mov_b32_e32 v4, v68
	v_mov_b32_e32 v5, v69
	v_mov_b32_e32 v2, v66
	v_mov_b32_e32 v3, v67
	v_mov_b32_e32 v40, v168
	v_mov_b32_e32 v41, v169
	v_mov_b32_e32 v38, v166
	v_mov_b32_e32 v39, v167
	v_mov_b32_e32 v32, v164
	v_mov_b32_e32 v33, v165
	v_mov_b32_e32 v30, v162
	v_mov_b32_e32 v31, v163
	v_mov_b32_e32 v140, v174
	v_mov_b32_e32 v141, v175
	v_mov_b32_e32 v36, v88
	v_mov_b32_e32 v37, v89
	v_mov_b32_e32 v28, v84
	v_mov_b32_e32 v29, v85
	v_mov_b32_e32 v34, v86
	v_mov_b32_e32 v35, v87
	v_mov_b32_e32 v26, v82
	v_mov_b32_e32 v27, v83
	v_mov_b32_e32 v20, v80
	v_mov_b32_e32 v21, v81
	v_mov_b32_e32 v16, v76
	v_mov_b32_e32 v17, v77
	v_mov_b32_e32 v8, v72
	v_mov_b32_e32 v9, v73
	v_mov_b32_e32 v18, v78
	v_mov_b32_e32 v19, v79
	v_mov_b32_e32 v14, v74
	v_mov_b32_e32 v15, v75
	v_mov_b32_e32 v6, v70
	v_mov_b32_e32 v7, v71
	v_mov_b32_e32 v154, v137
	v_mov_b32_e32 v62, v110
	v_mov_b32_e32 v63, v111
	v_mov_b32_e32 v64, v112
	v_mov_b32_e32 v65, v113
	v_mov_b32_e32 v54, v98
	v_mov_b32_e32 v55, v99
	v_mov_b32_e32 v56, v100
	v_mov_b32_e32 v57, v101
	v_mov_b32_e32 v46, v102
	v_mov_b32_e32 v47, v103
	v_mov_b32_e32 v48, v104
	v_mov_b32_e32 v49, v105
	v_mov_b32_e32 v42, v106
	v_mov_b32_e32 v43, v107
	v_mov_b32_e32 v44, v108
	v_mov_b32_e32 v45, v109
	v_mov_b32_e32 v50, v94
	v_mov_b32_e32 v51, v95
	v_mov_b32_e32 v58, v90
	v_mov_b32_e32 v59, v91
	v_mov_b32_e32 v60, v92
	v_mov_b32_e32 v61, v93
	v_mov_b32_e32 v52, v96
	v_mov_b32_e32 v53, v97
; #define LAS __attribute__((address_space(3)))
; __device__ __forceinline__ f32x4 mma16(const h16x8 a, const h16x8 b, const f32x4 c) { return __builtin_amdgcn_mfma_f32_16x16x32_f16(a, b, c, 0, 0, 0); }
; __device__ __forceinline__ void phase_gdn_scan(const int wid_s, CParams& p, LAS unsigned char* lds) {
;     ...
;         for (int n = 0; n < 64; ++n) {
;             const int tc0 = b * SEQ + n * 64;
;             const LAS h16* Sc = St + cur * (32 * 136); LAS h16* Sn = St + (cur ^ 1) * (32 * 136);
;             { const int nn = n + 1 < 64 ? n + 1 : n; SCAN_LOAD(wfn, uun, qfn, infn, kfn, egln, nn); }
;             {
;                 f32x4 acc = {0.f, 0.f, 0.f, 0.f};
; #pragma unroll
;                 for (int ks = 0; ks < 4; ++ks) acc = mma16(*(const LAS h16x8*)(Sc + (16 * vt + lr) * 136 + 32 * ks + 8 * lq), wf[ks], acc);
; #pragma unroll
;                 for (int r = 0; r < 4; ++r) Vnt[(16 * vt + 4 * lq + r) * 72 + 16 * wq + lr] = (h16)((float)uu[r] - acc[r]);
;             }
;             __syncthreads();
;             {
;                 f32x4 acc = {0.f, 0.f, 0.f, 0.f};
; #pragma unroll
;                 for (int ks = 0; ks < 4; ++ks) acc = mma16(qf[ks], *(const LAS h16x8*)(Sc + (16 * vt + lr) * 136 + 32 * ks + 8 * lq), acc);
; #pragma unroll
;                 for (int ks = 0; ks < 2; ++ks) acc = mma16(inf[ks], *(const LAS h16x8*)(Vnt + (16 * vt + lr) * 72 + 32 * ks + 8 * lq), acc);
; #pragma unroll
;                 for (int r = 0; r < 4; ++r) y[(size_t)(tc0 + 16 * wq + 4 * lq + r) * D + 512 + h * 128 + 32 * sl + 16 * vt + lr] = (h16)acc[r];
;             }
; #pragma unroll
;             for (int i = 0; i < 2; ++i) {
;                 f32x4 acc = st[i] * __expf(egl);
; #pragma unroll
;                 for (int ks = 0; ks < 2; ++ks) acc = mma16(*(const LAS h16x8*)(Vnt + (16 * vt + lr) * 72 + 32 * ks + 8 * lq), kf[i][ks], acc);
;                 st[i] = acc;
; #pragma unroll
;                 for (int r = 0; r < 4; ++r) Sn[(16 * vt + 4 * lq + r) * 136 + 16 * (2 * wq + i) + lr] = (h16)acc[r];
;             }
;             __syncthreads();
.Lscan_in_n:
	ds_read_b128 v[66:69], v117 offset:8704
	v_add_u32_e32 v70, s10, v119
	v_readlane_b32 s6, v253, 0
	s_add_i32 s18, s18, s6
	v_readlane_b32 s6, v253, 57
	s_add_i32 s17, s17, s6
	s_cmpk_gt_i32 s18, 0xff
	s_waitcnt lgkmcnt(0)
	v_mfma_f32_16x16x32_f16 v[62:65], v[66:69], v[62:65], 0
	ds_read_b128 v[66:69], v117 offset:8768
	s_waitcnt lgkmcnt(0)
	v_mfma_f32_16x16x32_f16 v[58:61], v[66:69], v[58:61], v[62:65]
	s_nop 4
	ds_read_b128 v[62:65], v117 offset:8832
	s_waitcnt lgkmcnt(0)
	v_mfma_f32_16x16x32_f16 v[54:57], v[62:65], v[54:57], v[58:61]
	s_nop 2
	ds_read_b128 v[58:61], v117 offset:8896
	s_waitcnt lgkmcnt(0)
	v_mfma_f32_16x16x32_f16 v[38:41], v[58:61], v[38:41], v[54:57]
	s_nop 2
	v_cvt_f32_f16_e32 v54, v140
	s_nop 3
	v_sub_f32_e32 v38, v54, v38
	v_cvt_f16_f32_e32 v38, v38
	ds_write_b16 v153, v38 offset:17408
	v_cvt_f32_f16_sdwa v38, v140 dst_sel:DWORD dst_unused:UNUSED_PAD src0_sel:WORD_1
	v_sub_f32_e32 v38, v38, v39
	v_cvt_f16_f32_e32 v38, v38
	ds_write_b16 v153, v38 offset:17552
	v_cvt_f32_f16_e32 v38, v141
	v_sub_f32_e32 v38, v38, v40
	v_cvt_f16_f32_e32 v38, v38
	ds_write_b16 v153, v38 offset:17696
	v_cvt_f32_f16_sdwa v38, v141 dst_sel:DWORD dst_unused:UNUSED_PAD src0_sel:WORD_1
	v_sub_f32_e32 v38, v38, v41
	v_cvt_f16_f32_e32 v38, v38
	ds_write_b16 v153, v38 offset:17840
	s_waitcnt lgkmcnt(0)
	s_barrier
	ds_read_b128 v[38:41], v117 offset:8704
	s_waitcnt lgkmcnt(0)
	v_mfma_f32_16x16x32_f16 v[38:41], v[50:53], v[38:41], 0
	ds_read_b128 v[50:53], v117 offset:8768
	s_waitcnt lgkmcnt(0)
	v_mfma_f32_16x16x32_f16 v[38:41], v[46:49], v[50:53], v[38:41]
	ds_read_b128 v[46:49], v117 offset:8832
	s_waitcnt lgkmcnt(0)
	v_mfma_f32_16x16x32_f16 v[38:41], v[42:45], v[46:49], v[38:41]
	ds_read_b128 v[42:45], v117 offset:8896
	s_waitcnt vmcnt(11) lgkmcnt(0)
	v_mfma_f32_16x16x32_f16 v[30:33], v[30:33], v[42:45], v[38:41]
	s_nop 4
	ds_read_b128 v[38:41], v135 offset:17408
	s_waitcnt vmcnt(10) lgkmcnt(0)
	v_mfma_f32_16x16x32_f16 v[34:37], v[34:37], v[38:41], v[30:33]
	s_nop 2
	ds_read_b128 v[30:33], v135 offset:17472
	s_waitcnt vmcnt(9) lgkmcnt(0)
	v_mfma_f32_16x16x32_f16 v[26:29], v[26:29], v[30:33], v[34:37]
	s_nop 2
	v_add_u32_e32 v34, 0xfc0, v70
	v_ashrrev_i32_e32 v35, 31, v34
	s_nop 2
	v_cvt_f16_f32_e32 v26, v26
	v_lshlrev_b64 v[34:35], 11, v[34:35]
	v_lshl_add_u64 v[34:35], v[138:139], 0, v[34:35]
	v_cvt_f16_f32_e32 v28, v28
	global_store_short v[34:35], v26, off
	v_cvt_f16_f32_e32 v34, v27
	v_add_u32_e32 v26, 0xfc1, v70
	v_ashrrev_i32_e32 v27, 31, v26
	v_lshlrev_b64 v[26:27], 11, v[26:27]
	v_lshl_add_u64 v[26:27], v[138:139], 0, v[26:27]
	global_store_short v[26:27], v34, off
	v_add_u32_e32 v26, 0xfc2, v70
	v_ashrrev_i32_e32 v27, 31, v26
	v_lshlrev_b64 v[26:27], 11, v[26:27]
	v_lshl_add_u64 v[26:27], v[138:139], 0, v[26:27]
	global_store_short v[26:27], v28, off
	v_cvt_f16_f32_e32 v28, v29
	v_add_u32_e32 v26, 0xfc3, v70
	v_ashrrev_i32_e32 v27, 31, v26
	v_lshlrev_b64 v[26:27], 11, v[26:27]
	v_lshl_add_u64 v[26:27], v[138:139], 0, v[26:27]
	global_store_short v[26:27], v28, off
	s_waitcnt vmcnt(8)
	v_mul_f32_e32 v26, 0x3fb8aa3b, v154
	v_exp_f32_e32 v26, v26
	s_nop 0
	v_pk_mul_f32 v[24:25], v[26:27], v[24:25] op_sel_hi:[0,1]
	v_pk_mul_f32 v[22:23], v[26:27], v[22:23] op_sel_hi:[0,1]
	v_pk_mul_f32 v[12:13], v[26:27], v[12:13] op_sel_hi:[0,1]
	v_pk_mul_f32 v[10:11], v[26:27], v[10:11] op_sel_hi:[0,1]
	v_mfma_f32_16x16x32_f16 v[18:21], v[38:41], v[18:21], v[22:25]
	v_mfma_f32_16x16x32_f16 v[14:17], v[30:33], v[14:17], v[18:21]
	s_nop 6
	v_add_u32_e32 v18, v148, v149
	v_cvt_f16_f32_e32 v14, v14
	ds_write_b16 v18, v14
	v_cvt_f16_f32_e32 v14, v15
	ds_write_b16 v18, v14 offset:272
	v_cvt_f16_f32_e32 v14, v16
	ds_write_b16 v18, v14 offset:544
	v_cvt_f16_f32_e32 v14, v17
	ds_write_b16 v18, v14 offset:816
	ds_read_b128 v[14:17], v135 offset:17408
	s_waitcnt lgkmcnt(0)
	v_mfma_f32_16x16x32_f16 v[6:9], v[14:17], v[6:9], v[10:13]
	s_nop 2
	ds_read_b128 v[10:13], v135 offset:17472
	s_waitcnt lgkmcnt(0)
	v_mfma_f32_16x16x32_f16 v[2:5], v[10:13], v[2:5], v[6:9]
	s_nop 7
	v_cvt_f16_f32_e32 v2, v2
	ds_write_b16 v18, v2 offset:32
	v_cvt_f16_f32_e32 v2, v3
	ds_write_b16 v18, v2 offset:304
	v_cvt_f16_f32_e32 v2, v4
	ds_write_b16 v18, v2 offset:576
	v_cvt_f16_f32_e32 v2, v5
	ds_write_b16 v18, v2 offset:848
	s_waitcnt lgkmcnt(0)
	s_barrier
	s_cbranch_scc0 .LBB0_1281
